# phase shadowing: layer-0 weight transposes run in step 0 on the 320 workgroups without mod_unit work; step 1 only does the input-row units
# speedup vs baseline: 1.0056x; 1.0007x over previous
.LBB0_609:
	v_readlane_b32 s25, v255, 27
	s_and_b64 vcc, exec, s[6:7]
	s_cbranch_vccz .LBB0_659
	s_cmp_lt_u32 s25, 11
	s_cbranch_scc0 .LBB0_659
	s_movk_i32 s100, 0x200
.Lcv_entry:
	v_readlane_b32 s6, v255, 9
	v_readlane_b32 s7, v255, 10
	s_mov_b64 s[4:5], s[0:1]
	v_mov_b32_e32 v14, v254
	s_andn2_b64 vcc, exec, s[6:7]
	s_cbranch_vccnz .LBB0_657
	s_load_dwordx2 s[6:7], s[4:5], 0x120
	v_lshlrev_b32_e32 v0, 3, v14
	v_and_b32_e32 v0, 0x3f8, v0
	v_lshlrev_b32_e32 v148, 1, v0
	v_lshlrev_b32_e32 v10, 4, v14
	s_waitcnt lgkmcnt(0)
	s_add_u32 s8, s6, 0x201000
	v_lshl_add_u64 v[2:3], s[6:7], 0, v[148:149]
	s_mov_b64 s[10:11], 0xe0c1000
	v_ashrrev_i32_e32 v11, 31, v10
	s_addc_u32 s9, s7, 0
	v_lshl_add_u64 v[8:9], v[2:3], 0, s[10:11]
	v_lshl_add_u64 v[2:3], v[10:11], 1, s[6:7]
	s_mov_b64 s[10:11], 0x2441000
	v_lshl_add_u64 v[12:13], v[2:3], 0, s[10:11]
	s_add_u32 s10, s6, 0x24a1000
	s_addc_u32 s11, s7, 0
	s_add_u32 s40, s6, 0x2481000
	s_addc_u32 s41, s7, 0
	s_add_u32 s44, s6, 0x2461000
	s_addc_u32 s45, s7, 0
	s_add_u32 s12, s6, 0xa01000
	s_addc_u32 s13, s7, 0
	s_add_u32 s28, s6, 0x2241000
	s_addc_u32 s29, s7, 0
	s_add_u32 s82, s6, 0x1f41000
	s_addc_u32 s83, s7, 0
	s_add_u32 s30, s6, 0x1201000
	s_addc_u32 s31, s7, 0
	v_lshlrev_b32_e32 v148, 2, v0
	v_readlane_b32 s84, v255, 0
	s_cmpk_eq_u32 s100, 0x140
	s_cbranch_scc1 .Lcv_modeT
	s_addk_i32 s84, 0x1160
	s_branch .LBB0_614
.Lcv_modeT:
	s_sub_i32 s84, s84, 0xc0
	s_branch .LBB0_614
.LBB0_613:
	s_add_i32 s84, s84, s100
	s_movk_i32 s101, 0x175f
	s_cmpk_eq_u32 s100, 0x140
	s_cselect_b32 s101, 0x115f, s101
	s_cmp_gt_i32 s84, s101
	s_cbranch_scc1 .LBB0_657

.LBB0_660:
	v_readlane_b32 s4, v255, 13
	v_readlane_b32 s5, v255, 14
	s_andn2_b64 vcc, exec, s[4:5]
	v_readlane_b32 s12, v255, 0
	s_cbranch_vccz .LBB0_664
	s_movk_i32 s100, 0x140
	v_writelane_b32 v255, s25, 27
	s_branch .Lcv_entry
